# Hyena conv: the lines of the short-conv fill's later load groups are touched up front so only one HBM round trip is exposed per batch pair
# baseline (speedup 1.0000x reference)
.LBB0_2052:
	v_mov_b32_e32 v32, v93
	s_or_b32 s26, s25, s24
	v_mbcnt_lo_u32_b32 v32, -1, v32
	v_mbcnt_hi_u32_b32 v32, -1, v32
	v_add_u32_e32 v32, s84, v32
	s_xor_b64 s[18:19], s[20:21], -1
	v_add_u32_e32 v57, s26, v32
	v_cmp_lt_i32_e64 s[4:5], 0, v32
	v_lshlrev_b32_e32 v59, 1, v57
	v_add_u32_e32 v0, 0x800, v59
	global_load_ushort v0, v0, s[48:49]
	v_add_u32_e32 v1, 0x2800, v59
	global_load_ushort v1, v1, s[48:49]
	v_add_u32_e32 v2, 0xa00, v59
	global_load_ushort v2, v2, s[48:49]
	v_add_u32_e32 v3, 0x2a00, v59
	global_load_ushort v3, v3, s[48:49]
	v_add_u32_e32 v4, 0xc00, v59
	global_load_ushort v4, v4, s[48:49]
	v_add_u32_e32 v5, 0x2c00, v59
	global_load_ushort v5, v5, s[48:49]
	v_add_u32_e32 v6, 0xe00, v59
	global_load_ushort v6, v6, s[48:49]
	v_add_u32_e32 v7, 0x2e00, v59
	global_load_ushort v7, v7, s[48:49]
	v_add_u32_e32 v8, 0x1000, v59
	global_load_ushort v8, v8, s[48:49]
	v_add_u32_e32 v9, 0x3000, v59
	global_load_ushort v9, v9, s[48:49]
	v_add_u32_e32 v10, 0x1200, v59
	global_load_ushort v10, v10, s[48:49]
	v_add_u32_e32 v11, 0x3200, v59
	global_load_ushort v11, v11, s[48:49]
	v_add_u32_e32 v12, 0x1400, v59
	global_load_ushort v12, v12, s[48:49]
	v_add_u32_e32 v13, 0x3400, v59
	global_load_ushort v13, v13, s[48:49]
	v_add_u32_e32 v14, 0x1600, v59
	global_load_ushort v14, v14, s[48:49]
	v_add_u32_e32 v15, 0x3600, v59
	global_load_ushort v15, v15, s[48:49]
	v_add_u32_e32 v16, 0x1800, v59
	global_load_ushort v16, v16, s[48:49]
	v_add_u32_e32 v17, 0x3800, v59
	global_load_ushort v17, v17, s[48:49]
	v_add_u32_e32 v18, 0x1a00, v59
	global_load_ushort v18, v18, s[48:49]
	v_add_u32_e32 v19, 0x3a00, v59
	global_load_ushort v19, v19, s[48:49]
	v_add_u32_e32 v20, 0x1c00, v59
	global_load_ushort v20, v20, s[48:49]
	v_add_u32_e32 v21, 0x3c00, v59
	global_load_ushort v21, v21, s[48:49]
	v_add_u32_e32 v22, 0x1e00, v59
	global_load_ushort v22, v22, s[48:49]
	v_add_u32_e32 v23, 0x3e00, v59
	global_load_ushort v23, v23, s[48:49]
	v_add_u32_e32 v35, 0x2002, v59
	v_subbrev_co_u32_e64 v33, vcc, 0, v57, s[4:5]
	v_add_u32_e32 v36, 2, v59
	v_add_u32_e32 v37, 0x2000, v59
	v_add_u32_e32 v39, 0x1fe, v59
	v_add_u32_e32 v40, 0x21fe, v59
	v_add_u32_e32 v41, 0x2202, v59
	v_add_u32_e32 v42, 0x202, v59
	v_add_u32_e32 v43, 0x2200, v59
	v_add_u32_e32 v45, 0x3fe, v59
	v_add_u32_e32 v46, 0x23fe, v59
	v_lshlrev_b32_e32 v33, 1, v33
	v_add_u32_e32 v38, 0x200, v59
	global_load_ushort v44, v35, s[48:49]
	s_nop 0
	global_load_ushort v35, v36, s[48:49]
	s_nop 0
	global_load_ushort v36, v37, s[48:49]
	s_nop 0
	global_load_ushort v37, v39, s[48:49]
	s_nop 0
	global_load_ushort v39, v38, s[48:49]
	v_add_u32_e32 v47, 0x2402, v59
	v_add_u32_e32 v48, 0x402, v59
	global_load_ushort v40, v40, s[48:49]
	s_nop 0
	global_load_ushort v49, v41, s[48:49]
	s_nop 0
	global_load_ushort v41, v42, s[48:49]
	s_nop 0
	global_load_ushort v42, v43, s[48:49]
	s_nop 0
	global_load_ushort v46, v46, s[48:49]
	s_nop 0
	global_load_ushort v50, v47, s[48:49]
	s_nop 0
	global_load_ushort v45, v45, s[48:49]
	v_add_u32_e32 v43, 0x2400, v59
	v_add_u32_e32 v34, 0x2000, v33
	v_add_u32_e32 v38, 0x400, v59
	global_load_ushort v47, v48, s[48:49]
	s_nop 0
	global_load_ushort v48, v43, s[48:49]
	global_load_ushort v51, v38, s[48:49]
	global_load_ushort v52, v59, s[48:49]
	s_nop 0
	global_load_ushort v33, v33, s[48:49]
	s_nop 0
	global_load_ushort v53, v34, s[48:49]
	global_load_dword v60, v93, s[6:7]
	global_load_dword v62, v93, s[16:17]
	global_load_dword v58, v93, s[12:13]
	global_load_dword v56, v93, s[14:15]
	v_add_u32_e32 v43, 0x602, v59
	v_add_u32_e32 v54, 0x2600, v59
	v_add_u32_e32 v34, 0x5fe, v59
	v_add_u32_e32 v38, 0x25fe, v59
	global_load_ushort v55, v43, s[48:49]
	s_nop 0
	global_load_ushort v54, v54, s[48:49]
	s_nop 0
	global_load_ushort v61, v34, s[48:49]
	global_load_ushort v63, v38, s[48:49]
	v_add_u32_e32 v34, 0x2602, v59
	global_load_ushort v65, v34, s[48:49]
	v_add_u32_e32 v34, 0x600, v59
	global_load_ushort v66, v34, s[48:49]
	v_cmp_gt_i32_e32 vcc, s92, v32
	v_mov_b32_e32 v32, 0x1000
	v_mov_b32_e32 v34, 0x1001
	v_cndmask_b32_e32 v82, v32, v34, vcc
	v_cndmask_b32_e64 v32, 0, 1.0, s[4:5]
	v_cndmask_b32_e64 v64, 0, 1.0, vcc
	s_waitcnt vmcnt(27)
	v_lshlrev_b32_e32 v34, 16, v44
	s_waitcnt vmcnt(26)
	v_lshlrev_b32_e32 v35, 16, v35
	s_waitcnt vmcnt(25)
	v_lshlrev_b32_e32 v38, 16, v36
	s_waitcnt vmcnt(22)
	v_lshlrev_b32_e32 v36, 16, v40
	s_waitcnt vmcnt(21)
	v_lshlrev_b32_e32 v40, 16, v49
	s_waitcnt vmcnt(18)
	v_lshlrev_b32_e32 v44, 16, v46
	s_waitcnt vmcnt(17)
	v_lshlrev_b32_e32 v46, 16, v50
	s_waitcnt vmcnt(13)
	v_lshlrev_b32_e32 v49, 16, v51
	s_waitcnt vmcnt(11)
	v_lshlrev_b32_e32 v51, 16, v33
	s_waitcnt vmcnt(10)
	v_lshlrev_b32_e32 v50, 16, v53
	v_pk_mul_f32 v[32:33], v[32:33], v[50:51] op_sel_hi:[0,1]
	v_lshlrev_b32_e32 v37, 16, v37
	v_lshlrev_b32_e32 v43, 16, v39
	v_lshlrev_b32_e32 v45, 16, v45
	v_lshlrev_b32_e32 v39, 16, v52
	v_lshlrev_b32_e32 v42, 16, v42
	s_waitcnt vmcnt(2)
	v_pk_fma_f32 v[32:33], v[60:61], v[32:33], v[62:63] op_sel_hi:[0,1,0]
	v_lshlrev_b32_e32 v48, 16, v48
	v_pk_fma_f32 v[36:37], v[60:61], v[36:37], v[62:63] op_sel_hi:[0,1,0]
	v_pk_fma_f32 v[44:45], v[60:61], v[44:45], v[62:63] op_sel_hi:[0,1,0]
	v_pk_fma_f32 v[32:33], v[58:59], v[38:39], v[32:33] op_sel_hi:[0,1,1]
	v_lshlrev_b32_e32 v47, 16, v47
	v_pk_fma_f32 v[36:37], v[58:59], v[42:43], v[36:37] op_sel_hi:[0,1,1]
	v_pk_fma_f32 v[42:43], v[58:59], v[48:49], v[44:45] op_sel_hi:[0,1,1]
	v_pk_fma_f32 v[38:39], v[56:57], v[34:35], v[32:33] op_sel_hi:[0,1,1]
	v_lshlrev_b32_e32 v33, 16, v61
	v_lshlrev_b32_e32 v32, 16, v63
	v_lshlrev_b32_e32 v41, 16, v41
	v_pk_fma_f32 v[34:35], v[56:57], v[46:47], v[42:43] op_sel_hi:[0,1,1]
	v_pk_fma_f32 v[32:33], v[60:61], v[32:33], v[62:63] op_sel_hi:[0,1,0]
	s_waitcnt vmcnt(0)
	v_lshlrev_b32_e32 v43, 16, v66
	v_lshlrev_b32_e32 v42, 16, v54
	v_pk_fma_f32 v[36:37], v[56:57], v[40:41], v[36:37] op_sel_hi:[0,1,1]
	v_lshlrev_b32_e32 v41, 16, v55
	v_lshlrev_b32_e32 v40, 16, v65
	v_pk_fma_f32 v[32:33], v[58:59], v[42:43], v[32:33] op_sel_hi:[0,1,1]
	v_pk_fma_f32 v[32:33], v[56:57], v[40:41], v[32:33] op_sel_hi:[0,1,1]
	v_add_u32_e32 v40, 0x800, v59
	v_add_u32_e32 v41, 0x7fe, v59
	v_add_u32_e32 v42, 0x27fe, v59
	v_add_u32_e32 v43, 0x2802, v59
	v_add_u32_e32 v44, 0x802, v59
	v_add_u32_e32 v45, 0x2800, v59
	v_add_u32_e32 v46, 0xa00, v59
	v_add_u32_e32 v47, 0x9fe, v59
	global_load_ushort v42, v42, s[48:49]
	s_nop 0
	global_load_ushort v48, v43, s[48:49]
	s_nop 0
	global_load_ushort v43, v44, s[48:49]
	s_nop 0
	global_load_ushort v44, v45, s[48:49]
	s_nop 0
	global_load_ushort v47, v47, s[48:49]
	s_nop 0
	global_load_ushort v50, v46, s[48:49]
	s_nop 0
	global_load_ushort v41, v41, s[48:49]
	s_nop 0
	global_load_ushort v45, v40, s[48:49]
	v_add_u32_e32 v40, 0x29fe, v59
	v_add_u32_e32 v46, 0x2a02, v59
	v_add_u32_e32 v49, 0xa02, v59
	v_add_u32_e32 v51, 0x2a00, v59
	v_add_u32_e32 v52, 0xc00, v59
	v_add_u32_e32 v53, 0xbfe, v59
	v_add_u32_e32 v54, 0x2bfe, v59
	v_add_u32_e32 v55, 0x2c02, v59
	v_add_u32_e32 v61, 0xc02, v59
	v_add_u32_e32 v63, 0x2c00, v59
	global_load_ushort v65, v40, s[48:49]
	global_load_ushort v66, v46, s[48:49]
	s_nop 0
	global_load_ushort v49, v49, s[48:49]
	s_nop 0
	global_load_ushort v67, v51, s[48:49]
	s_nop 0
	global_load_ushort v54, v54, s[48:49]
	s_nop 0
	global_load_ushort v68, v55, s[48:49]
	s_nop 0
	global_load_ushort v53, v53, s[48:49]
	s_nop 0
	global_load_ushort v69, v52, s[48:49]
	v_add_u32_e32 v40, 0xdfe, v59
	v_add_u32_e32 v46, 0x2dfe, v59
	v_add_u32_e32 v51, 0x2e02, v59
	v_add_u32_e32 v52, 0xe02, v59
	v_add_u32_e32 v55, 0x2e00, v59
	global_load_ushort v61, v61, s[48:49]
	s_nop 0
	global_load_ushort v63, v63, s[48:49]
	s_nop 0
	global_load_ushort v70, v52, s[48:49]
	global_load_ushort v72, v55, s[48:49]
	global_load_ushort v71, v40, s[48:49]
	global_load_ushort v73, v46, s[48:49]
	v_add_u32_e32 v40, 0xe00, v59
	global_load_ushort v74, v51, s[48:49]
	global_load_ushort v75, v40, s[48:49]
	s_waitcnt vmcnt(23)
	v_lshlrev_b32_e32 v40, 16, v42
	s_waitcnt vmcnt(22)
	v_lshlrev_b32_e32 v42, 16, v48
	s_waitcnt vmcnt(21)
	v_lshlrev_b32_e32 v43, 16, v43
	s_waitcnt vmcnt(20)
	v_lshlrev_b32_e32 v44, 16, v44
	s_waitcnt vmcnt(19)
	v_lshlrev_b32_e32 v47, 16, v47
	s_waitcnt vmcnt(18)
	v_lshlrev_b32_e32 v51, 16, v50
	s_waitcnt vmcnt(17)
	v_lshlrev_b32_e32 v41, 16, v41
	s_waitcnt vmcnt(16)
	v_lshlrev_b32_e32 v45, 16, v45
	s_waitcnt vmcnt(15)
	v_lshlrev_b32_e32 v46, 16, v65
	s_waitcnt vmcnt(14)
	v_lshlrev_b32_e32 v48, 16, v66
	s_waitcnt vmcnt(13)
	v_lshlrev_b32_e32 v49, 16, v49
	s_waitcnt vmcnt(12)
	v_lshlrev_b32_e32 v50, 16, v67
	s_waitcnt vmcnt(11)
	v_lshlrev_b32_e32 v52, 16, v54
	s_waitcnt vmcnt(10)
	v_lshlrev_b32_e32 v54, 16, v68
	s_waitcnt vmcnt(9)
	v_lshlrev_b32_e32 v53, 16, v53
	s_waitcnt vmcnt(8)
	v_lshlrev_b32_e32 v67, 16, v69
	s_waitcnt vmcnt(7)
	v_lshlrev_b32_e32 v55, 16, v61
	s_waitcnt vmcnt(6)
	v_lshlrev_b32_e32 v66, 16, v63
	v_pk_fma_f32 v[40:41], v[60:61], v[40:41], v[62:63] op_sel_hi:[0,1,0]
	s_waitcnt vmcnt(4)
	v_lshlrev_b32_e32 v72, 16, v72
	s_waitcnt vmcnt(3)
	v_lshlrev_b32_e32 v69, 16, v71
	s_waitcnt vmcnt(2)
	v_lshlrev_b32_e32 v68, 16, v73
	v_pk_fma_f32 v[46:47], v[60:61], v[46:47], v[62:63] op_sel_hi:[0,1,0]
	s_waitcnt vmcnt(0)
	v_lshlrev_b32_e32 v73, 16, v75
	v_pk_fma_f32 v[52:53], v[60:61], v[52:53], v[62:63] op_sel_hi:[0,1,0]
	v_pk_fma_f32 v[68:69], v[60:61], v[68:69], v[62:63] op_sel_hi:[0,1,0]
	v_lshlrev_b32_e32 v71, 16, v70
	v_lshlrev_b32_e32 v70, 16, v74
	v_pk_fma_f32 v[40:41], v[58:59], v[44:45], v[40:41] op_sel_hi:[0,1,1]
	v_pk_fma_f32 v[44:45], v[58:59], v[50:51], v[46:47] op_sel_hi:[0,1,1]
	v_pk_fma_f32 v[50:51], v[58:59], v[66:67], v[52:53] op_sel_hi:[0,1,1]
	v_pk_fma_f32 v[52:53], v[58:59], v[72:73], v[68:69] op_sel_hi:[0,1,1]
	v_pk_fma_f32 v[46:47], v[56:57], v[42:43], v[40:41] op_sel_hi:[0,1,1]
	v_pk_fma_f32 v[44:45], v[56:57], v[48:49], v[44:45] op_sel_hi:[0,1,1]
	v_pk_fma_f32 v[42:43], v[56:57], v[54:55], v[50:51] op_sel_hi:[0,1,1]
	v_pk_fma_f32 v[40:41], v[56:57], v[70:71], v[52:53] op_sel_hi:[0,1,1]
	v_add_u32_e32 v48, 0x1000, v59
	v_add_u32_e32 v49, 0xffe, v59
	v_add_u32_e32 v50, 0x2ffe, v59
	v_add_u32_e32 v51, 0x3002, v59
	v_add_u32_e32 v52, 0x1002, v59
	v_add_u32_e32 v53, 0x3000, v59
	v_add_u32_e32 v54, 0x1200, v59
	v_add_u32_e32 v55, 0x11fe, v59
	global_load_ushort v50, v50, s[48:49]
	s_nop 0
	global_load_ushort v61, v51, s[48:49]
	s_nop 0
	global_load_ushort v51, v52, s[48:49]
	s_nop 0
	global_load_ushort v52, v53, s[48:49]
	s_nop 0
	global_load_ushort v55, v55, s[48:49]
	s_nop 0
	global_load_ushort v63, v54, s[48:49]
	s_nop 0
	global_load_ushort v49, v49, s[48:49]
	s_nop 0
	global_load_ushort v53, v48, s[48:49]
	v_add_u32_e32 v48, 0x31fe, v59
	v_add_u32_e32 v54, 0x3202, v59
	v_add_u32_e32 v65, 0x1202, v59
	v_add_u32_e32 v66, 0x3200, v59
	v_add_u32_e32 v67, 0x1400, v59
	v_add_u32_e32 v68, 0x13fe, v59
	v_add_u32_e32 v70, 0x3402, v59
	v_add_u32_e32 v71, 0x1402, v59
	v_add_u32_e32 v69, 0x33fe, v59
	v_add_u32_e32 v72, 0x3400, v59
	global_load_ushort v73, v48, s[48:49]
	global_load_ushort v74, v54, s[48:49]
	s_nop 0
	global_load_ushort v65, v65, s[48:49]
	s_nop 0
	global_load_ushort v75, v66, s[48:49]
	global_load_ushort v76, v69, s[48:49]
	global_load_ushort v77, v70, s[48:49]
	s_nop 0
	global_load_ushort v70, v68, s[48:49]
	global_load_ushort v78, v67, s[48:49]
	v_add_u32_e32 v48, 0x15fe, v59
	v_add_u32_e32 v54, 0x35fe, v59
	v_add_u32_e32 v66, 0x3602, v59
	v_add_u32_e32 v67, 0x1602, v59
	v_add_u32_e32 v68, 0x3600, v59
	global_load_ushort v79, v71, s[48:49]
	global_load_ushort v80, v72, s[48:49]
	global_load_ushort v81, v67, s[48:49]
	global_load_ushort v83, v68, s[48:49]
	global_load_ushort v84, v48, s[48:49]
	global_load_ushort v85, v54, s[48:49]
	v_add_u32_e32 v48, 0x1600, v59
	global_load_ushort v86, v66, s[48:49]
	global_load_ushort v87, v48, s[48:49]
	s_waitcnt vmcnt(23)
	v_lshlrev_b32_e32 v48, 16, v50
	s_waitcnt vmcnt(22)
	v_lshlrev_b32_e32 v50, 16, v61
	s_waitcnt vmcnt(21)
	v_lshlrev_b32_e32 v51, 16, v51
	s_waitcnt vmcnt(20)
	v_lshlrev_b32_e32 v52, 16, v52
	s_waitcnt vmcnt(19)
	v_lshlrev_b32_e32 v55, 16, v55
	s_waitcnt vmcnt(18)
	v_lshlrev_b32_e32 v69, 16, v63
	s_waitcnt vmcnt(17)
	v_lshlrev_b32_e32 v49, 16, v49
	s_waitcnt vmcnt(16)
	v_lshlrev_b32_e32 v53, 16, v53
	v_pk_fma_f32 v[48:49], v[60:61], v[48:49], v[62:63] op_sel_hi:[0,1,0]
	v_pk_fma_f32 v[48:49], v[58:59], v[52:53], v[48:49] op_sel_hi:[0,1,1]
	s_waitcnt vmcnt(15)
	v_lshlrev_b32_e32 v54, 16, v73
	s_waitcnt vmcnt(14)
	v_lshlrev_b32_e32 v66, 16, v74
	v_pk_fma_f32 v[54:55], v[60:61], v[54:55], v[62:63] op_sel_hi:[0,1,0]
	s_waitcnt vmcnt(12)
	v_lshlrev_b32_e32 v68, 16, v75
	v_lshlrev_b32_e32 v67, 16, v65
	s_waitcnt vmcnt(10)
	v_lshlrev_b32_e32 v72, 16, v77
	s_waitcnt vmcnt(9)
	v_lshlrev_b32_e32 v71, 16, v70
	v_lshlrev_b32_e32 v70, 16, v76
	s_waitcnt vmcnt(7)
	v_lshlrev_b32_e32 v73, 16, v79
	v_lshlrev_b32_e32 v75, 16, v78
	s_waitcnt vmcnt(6)
	v_lshlrev_b32_e32 v74, 16, v80
	s_waitcnt vmcnt(5)
	v_lshlrev_b32_e32 v79, 16, v81
	s_waitcnt vmcnt(3)
	v_lshlrev_b32_e32 v77, 16, v84
	s_waitcnt vmcnt(2)
	v_lshlrev_b32_e32 v76, 16, v85
	v_lshlrev_b32_e32 v80, 16, v83
	s_waitcnt vmcnt(0)
	v_lshlrev_b32_e32 v81, 16, v87
	v_pk_fma_f32 v[70:71], v[60:61], v[70:71], v[62:63] op_sel_hi:[0,1,0]
	v_pk_fma_f32 v[76:77], v[60:61], v[76:77], v[62:63] op_sel_hi:[0,1,0]
	v_lshlrev_b32_e32 v78, 16, v86
	v_pk_fma_f32 v[52:53], v[58:59], v[68:69], v[54:55] op_sel_hi:[0,1,1]
	v_pk_fma_f32 v[68:69], v[58:59], v[74:75], v[70:71] op_sel_hi:[0,1,1]
	v_pk_fma_f32 v[70:71], v[58:59], v[80:81], v[76:77] op_sel_hi:[0,1,1]
	v_pk_fma_f32 v[54:55], v[56:57], v[50:51], v[48:49] op_sel_hi:[0,1,1]
	v_pk_fma_f32 v[52:53], v[56:57], v[66:67], v[52:53] op_sel_hi:[0,1,1]
	v_pk_fma_f32 v[50:51], v[56:57], v[72:73], v[68:69] op_sel_hi:[0,1,1]
	v_pk_fma_f32 v[48:49], v[56:57], v[78:79], v[70:71] op_sel_hi:[0,1,1]
	v_add_u32_e32 v61, 0x1800, v59
	v_add_u32_e32 v63, 0x17fe, v59
	v_add_u32_e32 v65, 0x37fe, v59
	v_add_u32_e32 v66, 0x3802, v59
	v_add_u32_e32 v67, 0x1802, v59
	v_add_u32_e32 v68, 0x3800, v59
	v_add_u32_e32 v69, 0x1a00, v59
	v_add_u32_e32 v70, 0x19fe, v59
	global_load_ushort v65, v65, s[48:49]
	s_nop 0
	global_load_ushort v71, v66, s[48:49]
	global_load_ushort v72, v67, s[48:49]
	global_load_ushort v73, v68, s[48:49]
	global_load_ushort v74, v70, s[48:49]
	global_load_ushort v76, v69, s[48:49]
	s_nop 0
	global_load_ushort v63, v63, s[48:49]
	s_nop 0
	global_load_ushort v61, v61, s[48:49]
	v_add_u32_e32 v66, 0x39fe, v59
	v_add_u32_e32 v67, 0x3a02, v59
	v_add_u32_e32 v68, 0x1a02, v59
	v_add_u32_e32 v69, 0x3a00, v59
	v_add_u32_e32 v70, 0x1c00, v59
	v_add_u32_e32 v75, 0x1bfe, v59
	v_add_u32_e32 v77, 0x3bfe, v59
	v_add_u32_e32 v78, 0x3c02, v59
	v_add_u32_e32 v79, 0x1c02, v59
	v_add_u32_e32 v59, 0x3c00, v59
	global_load_ushort v80, v79, s[48:49]
	s_nop 0
	global_load_ushort v59, v59, s[48:49]
	s_nop 0
	global_load_ushort v79, v66, s[48:49]
	global_load_ushort v81, v67, s[48:49]
	global_load_ushort v83, v68, s[48:49]
	global_load_ushort v84, v69, s[48:49]
	global_load_ushort v85, v77, s[48:49]
	global_load_ushort v86, v78, s[48:49]
	s_nop 0
	global_load_ushort v78, v75, s[48:49]
	global_load_ushort v87, v70, s[48:49]
	v_add_u32_e32 v66, 0xf00, v57
	v_lshlrev_b32_e32 v67, 1, v66
	v_addc_co_u32_e32 v57, vcc, v57, v139, vcc
	v_add_lshl_u32 v66, v82, v66, 1
	v_lshlrev_b32_e32 v57, 1, v57
	v_add_u32_e32 v69, 0x2000, v67
	global_load_ushort v88, v66, s[48:49]
	s_nop 0
	global_load_ushort v57, v57, s[48:49]
	v_add_u32_e32 v66, -2, v67
	v_add_u32_e32 v68, 0x1ffe, v67
	global_load_ushort v92, v69, s[48:49]
	global_load_ushort v89, v66, s[48:49]
	global_load_ushort v90, v68, s[48:49]
	global_load_ushort v91, v67, s[48:49]
	s_waitcnt vmcnt(23)
	v_lshlrev_b32_e32 v66, 16, v65
	s_waitcnt vmcnt(22)
	v_lshlrev_b32_e32 v68, 16, v71
	s_waitcnt vmcnt(21)
	v_lshlrev_b32_e32 v69, 16, v72
	s_waitcnt vmcnt(20)
	v_lshlrev_b32_e32 v70, 16, v73
	s_waitcnt vmcnt(19)
	v_lshlrev_b32_e32 v73, 16, v74
	s_waitcnt vmcnt(18)
	v_lshlrev_b32_e32 v77, 16, v76
	s_waitcnt vmcnt(17)
	v_lshlrev_b32_e32 v67, 16, v63
	s_waitcnt vmcnt(16)
	v_lshlrev_b32_e32 v71, 16, v61
	v_pk_fma_f32 v[66:67], v[60:61], v[66:67], v[62:63] op_sel_hi:[0,1,0]
	s_waitcnt vmcnt(14)
	v_pk_fma_f32 v[66:67], v[58:59], v[70:71], v[66:67] op_sel_hi:[0,1,1]
	s_waitcnt vmcnt(13)
	v_lshlrev_b32_e32 v72, 16, v79
	v_pk_fma_f32 v[72:73], v[60:61], v[72:73], v[62:63] op_sel_hi:[0,1,0]
	s_waitcnt vmcnt(11)
	v_lshlrev_b32_e32 v75, 16, v83
	s_waitcnt vmcnt(10)
	v_lshlrev_b32_e32 v76, 16, v84
	v_pk_fma_f32 v[70:71], v[58:59], v[76:77], v[72:73] op_sel_hi:[0,1,1]
	v_lshlrev_b32_e32 v82, 16, v59
	s_waitcnt vmcnt(7)
	v_lshlrev_b32_e32 v79, 16, v78
	v_lshlrev_b32_e32 v78, 16, v85
	v_pk_fma_f32 v[78:79], v[60:61], v[78:79], v[62:63] op_sel_hi:[0,1,0]
	s_waitcnt vmcnt(6)
	v_lshlrev_b32_e32 v83, 16, v87
	v_lshlrev_b32_e32 v74, 16, v81
	v_lshlrev_b32_e32 v81, 16, v80
	v_lshlrev_b32_e32 v80, 16, v86
	v_pk_fma_f32 v[72:73], v[58:59], v[82:83], v[78:79] op_sel_hi:[0,1,1]
	s_waitcnt vmcnt(5)
	v_lshlrev_b32_e32 v84, 16, v88
	s_waitcnt vmcnt(4)
	v_lshlrev_b32_e32 v85, 16, v57
	s_waitcnt vmcnt(2)
	v_lshlrev_b32_e32 v77, 16, v89
	s_waitcnt vmcnt(1)
	v_lshlrev_b32_e32 v76, 16, v90
	s_waitcnt vmcnt(0)
	v_lshlrev_b32_e32 v61, 16, v91
	v_pk_fma_f32 v[62:63], v[60:61], v[76:77], v[62:63] op_sel_hi:[0,1,0]
	v_lshlrev_b32_e32 v60, 16, v92
	v_pk_mul_f32 v[64:65], v[64:65], v[84:85] op_sel_hi:[0,1]
	v_pk_fma_f32 v[58:59], v[58:59], v[60:61], v[62:63] op_sel_hi:[0,1,1]
	v_pk_fma_f32 v[90:91], v[56:57], v[68:69], v[66:67] op_sel_hi:[0,1,1]
	v_pk_fma_f32 v[88:89], v[56:57], v[74:75], v[70:71] op_sel_hi:[0,1,1]
	v_pk_fma_f32 v[86:87], v[56:57], v[80:81], v[72:73] op_sel_hi:[0,1,1]
	v_pk_fma_f32 v[98:99], v[56:57], v[64:65], v[58:59] op_sel_hi:[0,1,1]
	s_mov_b64 s[22:23], -1
	s_mov_b32 s27, 0
	s_barrier
	s_branch .LBB0_2054
